# G_up: conv weights/biases staged into LDS by LDS-DMA at tile start (double buffered), epilogue reads them with ds_read instead of two exposed global round trips
# speedup vs baseline: 1.0055x; 1.0017x over previous
;     DI void operator()(const f32x4 (&acc)[2][2][4][2], const Unit& u, int wr, int wc, int fr, int fq) const {
;     ...
;             const int ca = colA + 4 * n;
;             const f32x4 wa0 = *(const f32x4*)(cw + ca), wa1 = *(const f32x4*)(cw + DFF2 + ca), wa2 = *(const f32x4*)(cw + 2 * DFF2 + ca), ba = *(const f32x4*)(cb + ca);
;             const f32x4 wg0 = *(const f32x4*)(cw + DFF + ca), wg1 = *(const f32x4*)(cw + DFF2 + DFF + ca), wg2 = *(const f32x4*)(cw + 2 * DFF2 + DFF + ca), bg = *(const f32x4*)(cb + DFF + ca);
.LBB0_109:
	v_lshrrev_b32_e32 v183, 6, v187
	v_readlane_b32 s46, v255, 2
	v_readlane_b32 s47, v255, 3
	v_readfirstlane_b32 s0, v183
	v_readlane_b32 s62, v255, 4
	v_readlane_b32 s63, v255, 5
	v_readlane_b32 s40, v254, 52
	v_readlane_b32 s88, v255, 1
	v_and_b32_e32 v183, 31, v231
	v_lshlrev_b32_e32 v183, 4, v183
	s_nop 3
	s_cmp_eq_u32 s0, 1
	s_cselect_b64 s[46:47], s[80:81], s[46:47]
	s_cmp_eq_u32 s0, 2
	s_cselect_b64 s[46:47], s[70:71], s[46:47]
	s_cmp_eq_u32 s0, 3
	s_cselect_b64 s[46:47], s[62:63], s[46:47]
	s_cmp_eq_u32 s0, 4
	s_cselect_b64 s[46:47], s[24:25], s[46:47]
	s_cmp_eq_u32 s0, 5
	s_cselect_b64 s[46:47], s[72:73], s[46:47]
	s_cmp_eq_u32 s0, 6
	s_cselect_b64 s[46:47], s[66:67], s[46:47]
	s_cmp_eq_u32 s0, 7
	s_cselect_b64 s[46:47], s[68:69], s[46:47]
	s_lshl_b32 s40, s40, 9
	s_add_u32 s46, s46, s40
	s_addc_u32 s47, s47, 0
	s_and_b32 s88, s88, 1
	s_lshl_b32 s88, s88, 12
	s_lshl_b32 s91, s0, 9
	s_add_i32 s88, s88, s91
	s_add_i32 m0, s88, 0x20100
	s_mov_b32 exec_lo, -1
	s_mov_b32 exec_hi, 0
	global_load_lds_dwordx4 v183, s[46:47]
	s_mov_b64 exec, -1
	v_add_u32_e32 v128, s61, v212
	v_add_u32_e32 v129, s27, v213
	s_mov_b32 s90, 0
	s_mov_b32 s44, -2

; DI unsigned pk2(float lo, float hi) { f32x2 v = {lo, hi}; return __builtin_bit_cast(unsigned, __builtin_convertvector(v, bf16x2v)); }
; DI float dpp_ror1(float v) { return __builtin_bit_cast(float, __builtin_amdgcn_update_dpp(0, __builtin_bit_cast(int, v), 0x121, 0xF, 0xF, false)); }
;     DI void operator()(const f32x4 (&acc)[2][2][4][2], const Unit& u, int wr, int wc, int fr, int fq) const {
;         const int colA = 128 * u.pn + 32 * wc + 8 * fq;
; #pragma unroll
;         for (int n = 0; n < 2; ++n) {
;             const int ca = colA + 4 * n;
;             const f32x4 wa0 = *(const f32x4*)(cw + ca), wa1 = *(const f32x4*)(cw + DFF2 + ca), wa2 = *(const f32x4*)(cw + 2 * DFF2 + ca), ba = *(const f32x4*)(cb + ca);
;             const f32x4 wg0 = *(const f32x4*)(cw + DFF + ca), wg1 = *(const f32x4*)(cw + DFF2 + DFF + ca), wg2 = *(const f32x4*)(cw + 2 * DFF2 + DFF + ca), bg = *(const f32x4*)(cb + DFF + ca);
; #pragma unroll
;             for (int ai = 0; ai < 2; ++ai) {
;                 const int sg = 4 * u.pm + 2 * ai + wr, row0 = 64 * sg;
; #pragma unroll
;                 for (int m = 0; m < 4; ++m) {
;                     const int rho = 16 * m + fr;
;                     const f32x4 ca_ = acc[ai][0][m][n], cg_ = acc[ai][1][m][n];
;                     const f32x4 ua_ = acc[ai][0][m > 0 ? m - 1 : 0][n], ug_ = acc[ai][1][m > 0 ? m - 1 : 0][n];
;                     const f32x4 da_ = acc[ai][0][m < 3 ? m + 1 : 3][n], dg_ = acc[ai][1][m < 3 ? m + 1 : 3][n];
;                     float o[4];
; #pragma unroll
;                     for (int j = 0; j < 4; ++j) {
;                         const float upa = dpp_ror1(fr == 15 ? ua_[j] : ca_[j]), dna = dpp_rol1(fr == 0 ? da_[j] : ca_[j]);
;                         const float upg = dpp_ror1(fr == 15 ? ug_[j] : cg_[j]), dng = dpp_rol1(fr == 0 ? dg_[j] : cg_[j]);
;                         const float va = wa0[j] * upa + wa1[j] * ca_[j] + wa2[j] * dna + ba[j];
;                         const float vg = wg0[j] * upg + wg1[j] * cg_[j] + wg2[j] * dng + bg[j];
;                         const float sgm = vg * __builtin_amdgcn_rcpf(1.f + __builtin_amdgcn_exp2f(-vg * LOG2E));
;                         o[j] = sgm * va;
;                     }
;                     if (rho >= 1 && rho <= 62) { u32x2 w; w.x = pk2(o[0], o[1]); w.y = pk2(o[2], o[3]); *(u32x2*)(ACT + (size_t)(row0 + rho) * DFF + ca) = w; }
.LBB0_113:
	v_readlane_b32 s0, v254, 52
	v_readlane_b32 s44, v255, 2
	v_readlane_b32 s45, v255, 3
	v_lshl_or_b32 v162, s0, 7, v211
	v_ashrrev_i32_e32 v163, 31, v162
	v_lshlrev_b64 v[148:149], 2, v[162:163]
	v_lshl_add_u64 v[164:165], s[44:45], 0, v[148:149]
	v_readlane_b32 s44, v255, 4
	v_readlane_b32 s45, v255, 5
	v_lshl_add_u64 v[132:133], s[80:81], 0, v[148:149]
	v_lshl_add_u64 v[134:135], s[70:71], 0, v[148:149]
	v_readlane_b32 s44, v255, 1
	s_nop 3
	s_and_b32 s44, s44, 1
	s_lshl_b32 s44, s44, 12
	s_add_i32 s44, s44, 0x20100
	v_lshl_add_u32 v166, v211, 2, s44
	v_lshl_add_u64 v[140:141], s[24:25], 0, v[148:149]
	v_lshl_add_u64 v[144:145], s[72:73], 0, v[148:149]
	ds_read_b128 v[128:131], v166
	ds_read_b128 v[156:159], v166 offset:512
	s_nop 0
	ds_read_b128 v[132:135], v166 offset:1024
	v_cndmask_b32_e64 v168, v124, v116, s[10:11]
	ds_read_b128 v[136:139], v166 offset:1536
	s_nop 0
	ds_read_b128 v[140:143], v166 offset:2048
	s_nop 0
	ds_read_b128 v[152:155], v166 offset:2560
	v_lshl_add_u64 v[144:145], s[66:67], 0, v[148:149]
	v_lshl_add_u64 v[148:149], s[68:69], 0, v[148:149]
	ds_read_b128 v[144:147], v166 offset:3072
	v_mov_b32_e32 v174, v185
	ds_read_b128 v[148:151], v166 offset:3584
	v_mov_b32_e32 v182, v185
	v_mov_b32_dpp v174, v168 row_ror:15 row_mask:0xf bank_mask:0xf
	v_cndmask_b32_e64 v168, v92, v84, s[10:11]
	s_lshl_b32 s0, s26, 2
	v_readlane_b32 s40, v254, 62
	v_mov_b32_dpp v182, v168 row_ror:15 row_mask:0xf bank_mask:0xf
	v_cndmask_b32_e64 v168, v125, v117, s[10:11]
	v_mov_b32_e32 v175, v185
	v_cndmask_b32_e64 v169, v126, v118, s[10:11]
	v_mov_b32_e32 v170, v185
	s_add_i32 s54, s0, s40
	v_mov_b32_dpp v175, v168 row_ror:15 row_mask:0xf bank_mask:0xf
	v_cndmask_b32_e64 v168, v93, v85, s[10:11]
	v_mov_b32_e32 v183, v185
	v_mov_b32_dpp v170, v169 row_ror:15 row_mask:0xf bank_mask:0xf
	v_cndmask_b32_e64 v169, v94, v86, s[10:11]
	v_mov_b32_e32 v176, v185
	v_cndmask_b32_e64 v177, v127, v119, s[10:11]
	v_mov_b32_e32 v171, v185
	s_lshl_b32 s90, s54, 6
	v_mov_b32_e32 v172, v185
	v_mov_b32_e32 v180, v185
	v_mov_b32_e32 v173, v185
	v_mov_b32_e32 v181, v185
	v_mov_b32_dpp v183, v168 row_ror:15 row_mask:0xf bank_mask:0xf
	v_mov_b32_e32 v168, v185
	v_mov_b32_e32 v178, v185
	v_mov_b32_dpp v176, v169 row_ror:15 row_mask:0xf bank_mask:0xf
	v_mov_b32_e32 v169, v185
	v_mov_b32_dpp v171, v177 row_ror:15 row_mask:0xf bank_mask:0xf
	v_mov_b32_e32 v179, v185
	v_cndmask_b32_e64 v194, v95, v87, s[10:11]
	v_mov_b32_e32 v177, v185
	v_mov_b32_dpp v172, v124 row_ror:1 row_mask:0xf bank_mask:0xf
	v_mov_b32_dpp v180, v92 row_ror:1 row_mask:0xf bank_mask:0xf
	v_mov_b32_dpp v173, v125 row_ror:1 row_mask:0xf bank_mask:0xf
	v_mov_b32_dpp v181, v93 row_ror:1 row_mask:0xf bank_mask:0xf
	v_mov_b32_dpp v168, v126 row_ror:1 row_mask:0xf bank_mask:0xf
	v_mov_b32_dpp v178, v94 row_ror:1 row_mask:0xf bank_mask:0xf
	v_mov_b32_dpp v169, v127 row_ror:1 row_mask:0xf bank_mask:0xf
	v_mov_b32_dpp v179, v95 row_ror:1 row_mask:0xf bank_mask:0xf
	v_mov_b32_dpp v177, v194 row_ror:15 row_mask:0xf bank_mask:0xf
	v_or_b32_e32 v215, s90, v160
	s_and_saveexec_b64 s[44:45], s[12:13]
	s_cbranch_execz .LBB0_115
	s_waitcnt lgkmcnt(0)
	v_pk_mul_f32 v[198:199], v[92:93], v[152:153]
	v_pk_mul_f32 v[196:197], v[124:125], v[156:157]
	v_pk_fma_f32 v[180:181], v[140:141], v[180:181], v[198:199]
	v_pk_fma_f32 v[172:173], v[128:129], v[172:173], v[196:197]
	v_pk_fma_f32 v[180:181], v[144:145], v[182:183], v[180:181]
	v_pk_fma_f32 v[172:173], v[132:133], v[174:175], v[172:173]
	v_pk_add_f32 v[180:181], v[148:149], v[180:181]
	v_pk_add_f32 v[172:173], v[136:137], v[172:173]
	v_mul_f32_e32 v182, 0xbfb8aa3b, v180
	v_exp_f32_e32 v198, v182
	v_mul_f32_e32 v182, 0xbfb8aa3b, v181
	v_exp_f32_e32 v199, v182
	v_pk_mul_f32 v[182:183], v[94:95], v[154:155]
	v_add_f32_e32 v198, 1.0, v198
	v_pk_fma_f32 v[178:179], v[142:143], v[178:179], v[182:183]
	v_add_f32_e32 v199, 1.0, v199
	v_pk_fma_f32 v[176:177], v[146:147], v[176:177], v[178:179]
	v_rcp_f32_e32 v198, v198
	v_pk_add_f32 v[176:177], v[150:151], v[176:177]
	v_rcp_f32_e32 v199, v199
	v_mul_f32_e32 v178, 0xbfb8aa3b, v176
	v_mul_f32_e32 v179, 0xbfb8aa3b, v177
	v_exp_f32_e32 v178, v178
	v_exp_f32_e32 v179, v179
	v_pk_mul_f32 v[174:175], v[180:181], v[198:199]
	v_pk_mul_f32 v[194:195], v[126:127], v[158:159]
	v_pk_mul_f32 v[172:173], v[172:173], v[174:175]
	v_add_f32_e32 v174, 1.0, v178
	v_add_f32_e32 v175, 1.0, v179
	v_rcp_f32_e32 v174, v174
	v_rcp_f32_e32 v175, v175
	v_pk_fma_f32 v[168:169], v[130:131], v[168:169], v[194:195]
	v_readlane_b32 s46, v254, 39
	v_pk_fma_f32 v[168:169], v[134:135], v[170:171], v[168:169]
	v_pk_mul_f32 v[170:171], v[176:177], v[174:175]
	v_pk_add_f32 v[168:169], v[138:139], v[168:169]
	v_readlane_b32 s47, v254, 40
	v_pk_mul_f32 v[168:169], v[168:169], v[170:171]
	s_movk_i32 s0, 0x2c00
	v_cvt_pk_bf16_f32 v171, v168, v169
	v_mov_b64_e32 v[168:169], s[46:47]
	v_mad_i64_i32 v[168:169], s[46:47], v215, s0, v[168:169]
	v_cvt_pk_bf16_f32 v170, v172, v173
	v_lshl_add_u64 v[168:169], v[162:163], 1, v[168:169]
	global_store_dwordx2 v[168:169], v[170:171], off

; DI unsigned pk2(float lo, float hi) { f32x2 v = {lo, hi}; return __builtin_bit_cast(unsigned, __builtin_convertvector(v, bf16x2v)); }
; DI float dpp_ror1(float v) { return __builtin_bit_cast(float, __builtin_amdgcn_update_dpp(0, __builtin_bit_cast(int, v), 0x121, 0xF, 0xF, false)); }
; DI float dpp_rol1(float v) { return __builtin_bit_cast(float, __builtin_amdgcn_update_dpp(0, __builtin_bit_cast(int, v), 0x12F, 0xF, 0xF, false)); }
;     DI void operator()(const f32x4 (&acc)[2][2][4][2], const Unit& u, int wr, int wc, int fr, int fq) const {
;     ...
;                 for (int m = 0; m < 4; ++m) {
;                     const int rho = 16 * m + fr;
;                     const f32x4 ca_ = acc[ai][0][m][n], cg_ = acc[ai][1][m][n];
;                     const f32x4 ua_ = acc[ai][0][m > 0 ? m - 1 : 0][n], ug_ = acc[ai][1][m > 0 ? m - 1 : 0][n];
;                     const f32x4 da_ = acc[ai][0][m < 3 ? m + 1 : 3][n], dg_ = acc[ai][1][m < 3 ? m + 1 : 3][n];
;                     float o[4];
; #pragma unroll
;                     for (int j = 0; j < 4; ++j) {
;                         const float upa = dpp_ror1(fr == 15 ? ua_[j] : ca_[j]), dna = dpp_rol1(fr == 0 ? da_[j] : ca_[j]);
;                         const float upg = dpp_ror1(fr == 15 ? ug_[j] : cg_[j]), dng = dpp_rol1(fr == 0 ? dg_[j] : cg_[j]);
;                         const float va = wa0[j] * upa + wa1[j] * ca_[j] + wa2[j] * dna + ba[j];
;                         const float vg = wg0[j] * upg + wg1[j] * cg_[j] + wg2[j] * dng + bg[j];
;                         const float sgm = vg * __builtin_amdgcn_rcpf(1.f + __builtin_amdgcn_exp2f(-vg * LOG2E));
;                         o[j] = sgm * va;
;                     }
;                     if (rho >= 1 && rho <= 62) { u32x2 w; w.x = pk2(o[0], o[1]); w.y = pk2(o[2], o[3]); *(u32x2*)(ACT + (size_t)(row0 + rho) * DFF + ca) = w; }
.LBB0_117:
	s_or_b64 exec, exec, s[56:57]
	v_cndmask_b32_e64 v169, v116, v124, s[6:7]
	v_mov_b32_e32 v168, v185
	v_mov_b32_e32 v170, v185
	v_mov_b32_e32 v172, v185
	v_mov_b32_dpp v168, v169 row_ror:1 row_mask:0xf bank_mask:0xf
	v_cndmask_b32_e64 v169, v116, v108, s[10:11]
	v_mov_b32_e32 v174, v185
	v_cndmask_b32_e64 v171, v117, v125, s[6:7]
	v_mov_b32_dpp v170, v169 row_ror:15 row_mask:0xf bank_mask:0xf
	v_cndmask_b32_e64 v169, v84, v92, s[6:7]
	v_cndmask_b32_e64 v173, v117, v109, s[10:11]
	v_cndmask_b32_e64 v175, v85, v93, s[6:7]
	v_mov_b32_dpp v172, v169 row_ror:1 row_mask:0xf bank_mask:0xf
	v_cndmask_b32_e64 v169, v84, v76, s[10:11]
	v_cndmask_b32_e64 v176, v85, v77, s[10:11]
	s_waitcnt lgkmcnt(0)
	v_pk_mul_f32 v[200:201], v[84:85], v[152:153]
	v_mov_b32_dpp v174, v169 row_ror:15 row_mask:0xf bank_mask:0xf
	v_mov_b32_e32 v169, v185
	v_pk_mul_f32 v[196:197], v[116:117], v[156:157]
	v_cndmask_b32_e64 v177, v118, v126, s[6:7]
	v_mov_b32_dpp v169, v171 row_ror:1 row_mask:0xf bank_mask:0xf
	v_mov_b32_e32 v171, v185
	v_pk_fma_f32 v[168:169], v[128:129], v[168:169], v[196:197]
	v_mov_b32_e32 v178, v185
	v_mov_b32_dpp v171, v173 row_ror:15 row_mask:0xf bank_mask:0xf
	v_mov_b32_e32 v173, v185
	v_pk_fma_f32 v[168:169], v[132:133], v[170:171], v[168:169]
	v_mov_b32_e32 v180, v185
	v_mov_b32_dpp v173, v175 row_ror:1 row_mask:0xf bank_mask:0xf
	v_mov_b32_e32 v175, v185
	v_pk_fma_f32 v[172:173], v[140:141], v[172:173], v[200:201]
	v_mov_b32_e32 v182, v185
	v_mov_b32_dpp v175, v176 row_ror:15 row_mask:0xf bank_mask:0xf
	v_pk_fma_f32 v[172:173], v[144:145], v[174:175], v[172:173]
	v_mov_b32_e32 v176, v185
	v_pk_add_f32 v[172:173], v[148:149], v[172:173]
	v_cndmask_b32_e64 v179, v119, v127, s[6:7]
	v_mul_f32_e32 v174, 0xbfb8aa3b, v172
	v_mul_f32_e32 v170, 0xbfb8aa3b, v173
	v_exp_f32_e32 v174, v174
	v_exp_f32_e32 v170, v170
	v_mov_b32_dpp v176, v177 row_ror:1 row_mask:0xf bank_mask:0xf
	v_cndmask_b32_e64 v177, v118, v110, s[10:11]
	v_add_f32_e32 v174, 1.0, v174
	v_add_f32_e32 v170, 1.0, v170
	v_mov_b32_dpp v178, v177 row_ror:15 row_mask:0xf bank_mask:0xf
	v_cndmask_b32_e64 v177, v86, v94, s[6:7]
	v_rcp_f32_e32 v174, v174
	v_rcp_f32_e32 v175, v170
	v_mov_b32_dpp v180, v177 row_ror:1 row_mask:0xf bank_mask:0xf
	v_cndmask_b32_e64 v177, v86, v78, s[10:11]
	v_cndmask_b32_e64 v181, v119, v111, s[10:11]
	v_cndmask_b32_e64 v183, v87, v95, s[6:7]
	v_mov_b32_dpp v182, v177 row_ror:15 row_mask:0xf bank_mask:0xf
	v_mov_b32_e32 v177, v185
	v_cndmask_b32_e64 v194, v87, v79, s[10:11]
	v_pk_mul_f32 v[198:199], v[86:87], v[154:155]
	v_mov_b32_dpp v177, v179 row_ror:1 row_mask:0xf bank_mask:0xf
	v_mov_b32_e32 v179, v185
	v_pk_add_f32 v[168:169], v[136:137], v[168:169]
	v_pk_mul_f32 v[170:171], v[172:173], v[174:175]
	v_mov_b32_dpp v179, v181 row_ror:15 row_mask:0xf bank_mask:0xf
	v_mov_b32_e32 v181, v185
	v_pk_mul_f32 v[168:169], v[168:169], v[170:171]
	v_readlane_b32 s46, v254, 39
	v_mov_b32_dpp v181, v183 row_ror:1 row_mask:0xf bank_mask:0xf
	v_mov_b32_e32 v183, v185
	v_pk_fma_f32 v[170:171], v[142:143], v[180:181], v[198:199]
	v_readlane_b32 s47, v254, 40
	v_mov_b32_dpp v183, v194 row_ror:15 row_mask:0xf bank_mask:0xf
	v_pk_fma_f32 v[170:171], v[146:147], v[182:183], v[170:171]
	v_pk_mul_f32 v[194:195], v[118:119], v[158:159]
	v_pk_add_f32 v[170:171], v[150:151], v[170:171]
	v_pk_fma_f32 v[174:175], v[130:131], v[176:177], v[194:195]
	v_mul_f32_e32 v172, 0xbfb8aa3b, v170
	v_mul_f32_e32 v173, 0xbfb8aa3b, v171
	v_exp_f32_e32 v172, v172
	v_exp_f32_e32 v173, v173
	v_pk_fma_f32 v[174:175], v[134:135], v[178:179], v[174:175]
	s_movk_i32 s0, 0x2c00
	v_add_f32_e32 v172, 1.0, v172
	v_add_f32_e32 v173, 1.0, v173
	v_rcp_f32_e32 v172, v172
	v_rcp_f32_e32 v173, v173
	v_pk_add_f32 v[174:175], v[138:139], v[174:175]
	v_lshlrev_b64 v[176:177], 1, v[162:163]
	v_mov_b32_e32 v178, v185
	v_pk_mul_f32 v[170:171], v[170:171], v[172:173]
	v_cvt_pk_bf16_f32 v172, v168, v169
	v_pk_mul_f32 v[170:171], v[174:175], v[170:171]
	v_or_b32_e32 v168, s90, v208
	v_cvt_pk_bf16_f32 v173, v170, v171
	v_mov_b64_e32 v[170:171], s[46:47]
	v_mad_i64_i32 v[168:169], s[46:47], v168, s0, v[170:171]
	v_lshl_add_u64 v[168:169], v[168:169], 0, v[176:177]
	global_store_dwordx2 v[168:169], v[172:173], off
	v_cndmask_b32_e64 v173, v108, v116, s[6:7]
	v_mov_b32_e32 v172, v185
	v_mov_b32_e32 v174, v185
	v_mov_b32_e32 v180, v185
	v_mov_b32_dpp v172, v173 row_ror:1 row_mask:0xf bank_mask:0xf
	v_cndmask_b32_e64 v173, v108, v100, s[10:11]
	v_cndmask_b32_e64 v175, v109, v117, s[6:7]
	v_cndmask_b32_e64 v179, v109, v101, s[10:11]
	v_mov_b32_dpp v174, v173 row_ror:15 row_mask:0xf bank_mask:0xf
	v_cndmask_b32_e64 v173, v76, v84, s[6:7]
	v_cndmask_b32_e64 v181, v77, v85, s[6:7]
	v_cndmask_b32_e64 v182, v77, v69, s[10:11]
	v_mov_b32_dpp v178, v173 row_ror:1 row_mask:0xf bank_mask:0xf
	v_cndmask_b32_e64 v173, v76, v68, s[10:11]
	v_pk_mul_f32 v[202:203], v[76:77], v[152:153]
	v_pk_mul_f32 v[218:219], v[108:109], v[156:157]
	v_mov_b32_dpp v180, v173 row_ror:15 row_mask:0xf bank_mask:0xf
	v_mov_b32_e32 v173, v185
	v_cndmask_b32_e64 v183, v110, v118, s[6:7]
	v_mov_b32_e32 v194, v185
	v_mov_b32_dpp v173, v175 row_ror:1 row_mask:0xf bank_mask:0xf
	v_mov_b32_e32 v175, v185
	v_pk_fma_f32 v[172:173], v[128:129], v[172:173], v[218:219]
	v_mov_b32_e32 v196, v185
	v_mov_b32_dpp v175, v179 row_ror:15 row_mask:0xf bank_mask:0xf
	v_mov_b32_e32 v179, v185
	v_pk_fma_f32 v[172:173], v[132:133], v[174:175], v[172:173]
	v_mov_b32_e32 v198, v185
	v_mov_b32_dpp v179, v181 row_ror:1 row_mask:0xf bank_mask:0xf
	v_mov_b32_e32 v181, v185
	v_pk_fma_f32 v[178:179], v[140:141], v[178:179], v[202:203]
	v_cndmask_b32_e64 v195, v111, v119, s[6:7]
; DI unsigned pk2(float lo, float hi) { f32x2 v = {lo, hi}; return __builtin_bit_cast(unsigned, __builtin_convertvector(v, bf16x2v)); }
; DI float dpp_ror1(float v) { return __builtin_bit_cast(float, __builtin_amdgcn_update_dpp(0, __builtin_bit_cast(int, v), 0x121, 0xF, 0xF, false)); }
; DI float dpp_rol1(float v) { return __builtin_bit_cast(float, __builtin_amdgcn_update_dpp(0, __builtin_bit_cast(int, v), 0x12F, 0xF, 0xF, false)); }
;     DI void operator()(const f32x4 (&acc)[2][2][4][2], const Unit& u, int wr, int wc, int fr, int fq) const {
;     ...
;                 for (int m = 0; m < 4; ++m) {
;                     const int rho = 16 * m + fr;
;                     const f32x4 ca_ = acc[ai][0][m][n], cg_ = acc[ai][1][m][n];
;                     const f32x4 ua_ = acc[ai][0][m > 0 ? m - 1 : 0][n], ug_ = acc[ai][1][m > 0 ? m - 1 : 0][n];
;                     const f32x4 da_ = acc[ai][0][m < 3 ? m + 1 : 3][n], dg_ = acc[ai][1][m < 3 ? m + 1 : 3][n];
;                     float o[4];
; #pragma unroll
;                     for (int j = 0; j < 4; ++j) {
;                         const float upa = dpp_ror1(fr == 15 ? ua_[j] : ca_[j]), dna = dpp_rol1(fr == 0 ? da_[j] : ca_[j]);
;                         const float upg = dpp_ror1(fr == 15 ? ug_[j] : cg_[j]), dng = dpp_rol1(fr == 0 ? dg_[j] : cg_[j]);
;                         const float va = wa0[j] * upa + wa1[j] * ca_[j] + wa2[j] * dna + ba[j];
;                         const float vg = wg0[j] * upg + wg1[j] * cg_[j] + wg2[j] * dng + bg[j];
;                         const float sgm = vg * __builtin_amdgcn_rcpf(1.f + __builtin_amdgcn_exp2f(-vg * LOG2E));
;                         o[j] = sgm * va;
;                     }
;                     if (rho >= 1 && rho <= 62) { u32x2 w; w.x = pk2(o[0], o[1]); w.y = pk2(o[2], o[3]); *(u32x2*)(ACT + (size_t)(row0 + rho) * DFF + ca) = w; }
	v_mov_b32_dpp v181, v182 row_ror:15 row_mask:0xf bank_mask:0xf
	v_pk_fma_f32 v[178:179], v[144:145], v[180:181], v[178:179]
	v_mov_b32_e32 v182, v185
	v_pk_add_f32 v[178:179], v[148:149], v[178:179]
	v_cndmask_b32_e64 v197, v111, v103, s[10:11]
	v_mul_f32_e32 v180, 0xbfb8aa3b, v178
	v_mul_f32_e32 v174, 0xbfb8aa3b, v179
	v_exp_f32_e32 v180, v180
	v_exp_f32_e32 v174, v174
	v_mov_b32_dpp v182, v183 row_ror:1 row_mask:0xf bank_mask:0xf
	v_cndmask_b32_e64 v183, v110, v102, s[10:11]
	v_add_f32_e32 v180, 1.0, v180
	v_add_f32_e32 v174, 1.0, v174
	v_mov_b32_dpp v194, v183 row_ror:15 row_mask:0xf bank_mask:0xf
	v_cndmask_b32_e64 v183, v78, v86, s[6:7]
	v_rcp_f32_e32 v180, v180
	v_rcp_f32_e32 v181, v174
	v_mov_b32_dpp v196, v183 row_ror:1 row_mask:0xf bank_mask:0xf
	v_cndmask_b32_e64 v183, v78, v70, s[10:11]
	v_cndmask_b32_e64 v199, v79, v87, s[6:7]
	v_cndmask_b32_e64 v200, v79, v71, s[10:11]
	v_mov_b32_dpp v198, v183 row_ror:15 row_mask:0xf bank_mask:0xf
	v_mov_b32_e32 v183, v185
	v_pk_add_f32 v[172:173], v[136:137], v[172:173]
	v_pk_mul_f32 v[174:175], v[178:179], v[180:181]
	v_mov_b32_dpp v183, v195 row_ror:1 row_mask:0xf bank_mask:0xf
	v_mov_b32_e32 v195, v185
	v_pk_mul_f32 v[172:173], v[172:173], v[174:175]
	v_pk_mul_f32 v[202:203], v[110:111], v[158:159]
	v_mov_b32_dpp v195, v197 row_ror:15 row_mask:0xf bank_mask:0xf
	v_mov_b32_e32 v197, v185
	v_pk_fma_f32 v[180:181], v[130:131], v[182:183], v[202:203]
	v_mov_b32_e32 v182, v185
	v_mov_b32_dpp v197, v199 row_ror:1 row_mask:0xf bank_mask:0xf
	v_mov_b32_e32 v199, v185
	v_pk_fma_f32 v[180:181], v[134:135], v[194:195], v[180:181]
	v_cndmask_b32_e64 v195, v71, v79, s[6:7]
	v_mov_b32_dpp v199, v200 row_ror:15 row_mask:0xf bank_mask:0xf
	v_pk_mul_f32 v[200:201], v[78:79], v[154:155]
	v_pk_add_f32 v[180:181], v[138:139], v[180:181]
	v_pk_fma_f32 v[174:175], v[142:143], v[196:197], v[200:201]
	v_mov_b32_e32 v196, v185
	v_pk_fma_f32 v[174:175], v[146:147], v[198:199], v[174:175]
	v_mov_b32_e32 v197, v185
	v_pk_add_f32 v[174:175], v[150:151], v[174:175]
	v_mov_b32_e32 v183, v185
	v_mul_f32_e32 v178, 0xbfb8aa3b, v174
	v_mul_f32_e32 v179, 0xbfb8aa3b, v175
	v_exp_f32_e32 v178, v178
	v_exp_f32_e32 v179, v179
	v_mov_b32_e32 v198, v185
	v_mov_b32_e32 v199, v185
	v_add_f32_e32 v178, 1.0, v178
	v_add_f32_e32 v179, 1.0, v179
	v_rcp_f32_e32 v178, v178
	v_rcp_f32_e32 v179, v179
	v_mov_b32_e32 v194, v185
	v_mov_b32_dpp v183, v195 row_ror:1 row_mask:0xf bank_mask:0xf
	v_mov_b32_e32 v195, v185
	v_pk_mul_f32 v[174:175], v[174:175], v[178:179]
	v_cvt_pk_bf16_f32 v178, v172, v173
	v_or_b32_e32 v172, s90, v209
	v_pk_mul_f32 v[174:175], v[180:181], v[174:175]
	v_mad_i64_i32 v[170:171], s[46:47], v172, s0, v[170:171]
	v_cvt_pk_bf16_f32 v179, v174, v175
	v_lshl_add_u64 v[172:173], v[170:171], 0, v[176:177]
	global_store_dwordx2 v[172:173], v[178:179], off
	v_cndmask_b32_e64 v170, v100, v108, s[6:7]
	v_mov_b32_e32 v178, v185
	v_mov_b32_e32 v179, v185
	v_cndmask_b32_e64 v171, v102, v110, s[6:7]
	v_mov_b32_dpp v178, v170 row_ror:1 row_mask:0xf bank_mask:0xf
	v_cndmask_b32_e64 v170, v68, v76, s[6:7]
	v_cndmask_b32_e64 v175, v103, v111, s[6:7]
	v_mov_b32_e32 v180, v185
	v_mov_b32_dpp v196, v170 row_ror:1 row_mask:0xf bank_mask:0xf
	v_cndmask_b32_e64 v170, v101, v109, s[6:7]
	v_mov_b32_e32 v181, v185
	v_mov_b32_e32 v174, v185
	v_mov_b32_dpp v179, v170 row_ror:1 row_mask:0xf bank_mask:0xf
	v_cndmask_b32_e64 v170, v69, v77, s[6:7]
	s_movk_i32 s40, 0x2c00
	v_mov_b32_dpp v180, v100 row_ror:15 row_mask:0xf bank_mask:0xf
	v_mov_b32_dpp v197, v170 row_ror:1 row_mask:0xf bank_mask:0xf
	v_mov_b32_e32 v170, v185
	v_mov_b32_dpp v198, v68 row_ror:15 row_mask:0xf bank_mask:0xf
	v_mov_b32_dpp v181, v101 row_ror:15 row_mask:0xf bank_mask:0xf
	v_mov_b32_dpp v170, v171 row_ror:1 row_mask:0xf bank_mask:0xf
	v_cndmask_b32_e64 v171, v70, v78, s[6:7]
	v_mov_b32_dpp v199, v69 row_ror:15 row_mask:0xf bank_mask:0xf
	v_mov_b32_dpp v174, v102 row_ror:15 row_mask:0xf bank_mask:0xf
	v_mov_b32_dpp v182, v171 row_ror:1 row_mask:0xf bank_mask:0xf
	v_mov_b32_e32 v171, v185
	v_mov_b32_dpp v194, v70 row_ror:15 row_mask:0xf bank_mask:0xf
	v_mov_b32_dpp v195, v71 row_ror:15 row_mask:0xf bank_mask:0xf
	v_mov_b32_dpp v171, v175 row_ror:1 row_mask:0xf bank_mask:0xf
	v_mov_b32_e32 v175, v185
	v_or_b32_e32 v217, s90, v210
	s_nop 0
	v_mov_b32_dpp v175, v103 row_ror:15 row_mask:0xf bank_mask:0xf
	s_and_saveexec_b64 vcc, s[8:9]
	v_readlane_b32 s62, v254, 14
	s_movk_i32 s63, 0x7fff
	s_cbranch_execz .LBB0_119
	v_pk_mul_f32 v[218:219], v[68:69], v[152:153]
	v_pk_mul_f32 v[202:203], v[100:101], v[156:157]
	v_pk_fma_f32 v[196:197], v[140:141], v[196:197], v[218:219]
	v_pk_fma_f32 v[178:179], v[128:129], v[178:179], v[202:203]
	v_pk_fma_f32 v[196:197], v[144:145], v[198:199], v[196:197]
	v_pk_fma_f32 v[178:179], v[132:133], v[180:181], v[178:179]
	v_pk_add_f32 v[196:197], v[148:149], v[196:197]
	v_pk_add_f32 v[178:179], v[136:137], v[178:179]
	v_mul_f32_e32 v198, 0xbfb8aa3b, v196
	v_exp_f32_e32 v218, v198
	v_mul_f32_e32 v198, 0xbfb8aa3b, v197
	v_exp_f32_e32 v219, v198
	v_pk_mul_f32 v[198:199], v[70:71], v[154:155]
	v_add_f32_e32 v218, 1.0, v218
	v_pk_fma_f32 v[182:183], v[142:143], v[182:183], v[198:199]
	v_add_f32_e32 v219, 1.0, v219
	v_pk_fma_f32 v[182:183], v[146:147], v[194:195], v[182:183]
	v_rcp_f32_e32 v218, v218
	v_pk_add_f32 v[182:183], v[150:151], v[182:183]
	v_rcp_f32_e32 v219, v219
	v_mul_f32_e32 v194, 0xbfb8aa3b, v182
	v_mul_f32_e32 v195, 0xbfb8aa3b, v183
	v_exp_f32_e32 v194, v194
	v_exp_f32_e32 v195, v195
	v_pk_mul_f32 v[180:181], v[196:197], v[218:219]
	v_pk_mul_f32 v[200:201], v[102:103], v[158:159]
	v_pk_mul_f32 v[178:179], v[178:179], v[180:181]
	v_add_f32_e32 v180, 1.0, v194
	v_add_f32_e32 v181, 1.0, v195
	v_rcp_f32_e32 v180, v180
	v_rcp_f32_e32 v181, v181
	v_pk_fma_f32 v[170:171], v[130:131], v[170:171], v[200:201]
	v_readlane_b32 s46, v254, 39
	v_pk_fma_f32 v[170:171], v[134:135], v[174:175], v[170:171]
	v_pk_mul_f32 v[174:175], v[182:183], v[180:181]
	v_pk_add_f32 v[170:171], v[138:139], v[170:171]
	v_readlane_b32 s47, v254, 40
	v_pk_mul_f32 v[170:171], v[170:171], v[174:175]
	v_cvt_pk_bf16_f32 v174, v178, v179
	v_cvt_pk_bf16_f32 v175, v170, v171
	v_mov_b64_e32 v[170:171], s[46:47]
	v_mad_i64_i32 v[170:171], s[46:47], v217, s40, v[170:171]
	v_lshl_add_u64 v[170:171], v[162:163], 1, v[170:171]
	global_store_dwordx2 v[170:171], v[174:175], off

; DI unsigned pk2(float lo, float hi) { f32x2 v = {lo, hi}; return __builtin_bit_cast(unsigned, __builtin_convertvector(v, bf16x2v)); }
; DI float dpp_ror1(float v) { return __builtin_bit_cast(float, __builtin_amdgcn_update_dpp(0, __builtin_bit_cast(int, v), 0x121, 0xF, 0xF, false)); }
;     DI void operator()(const f32x4 (&acc)[2][2][4][2], const Unit& u, int wr, int wc, int fr, int fq) const {
;     ...
;         for (int n = 0; n < 2; ++n) {
;             const int ca = colA + 4 * n;
;             const f32x4 wa0 = *(const f32x4*)(cw + ca), wa1 = *(const f32x4*)(cw + DFF2 + ca), wa2 = *(const f32x4*)(cw + 2 * DFF2 + ca), ba = *(const f32x4*)(cb + ca);
;             const f32x4 wg0 = *(const f32x4*)(cw + DFF + ca), wg1 = *(const f32x4*)(cw + DFF2 + DFF + ca), wg2 = *(const f32x4*)(cw + 2 * DFF2 + DFF + ca), bg = *(const f32x4*)(cb + DFF + ca);
; #pragma unroll
;             for (int ai = 0; ai < 2; ++ai) {
;                 const int sg = 4 * u.pm + 2 * ai + wr, row0 = 64 * sg;
; #pragma unroll
;                 for (int m = 0; m < 4; ++m) {
;                     const int rho = 16 * m + fr;
;                     const f32x4 ca_ = acc[ai][0][m][n], cg_ = acc[ai][1][m][n];
;                     const f32x4 ua_ = acc[ai][0][m > 0 ? m - 1 : 0][n], ug_ = acc[ai][1][m > 0 ? m - 1 : 0][n];
;                     const f32x4 da_ = acc[ai][0][m < 3 ? m + 1 : 3][n], dg_ = acc[ai][1][m < 3 ? m + 1 : 3][n];
;                     float o[4];
; #pragma unroll
;                     for (int j = 0; j < 4; ++j) {
;                         const float upa = dpp_ror1(fr == 15 ? ua_[j] : ca_[j]), dna = dpp_rol1(fr == 0 ? da_[j] : ca_[j]);
;                         const float upg = dpp_ror1(fr == 15 ? ug_[j] : cg_[j]), dng = dpp_rol1(fr == 0 ? dg_[j] : cg_[j]);
;                         const float va = wa0[j] * upa + wa1[j] * ca_[j] + wa2[j] * dna + ba[j];
;                         const float vg = wg0[j] * upg + wg1[j] * cg_[j] + wg2[j] * dng + bg[j];
;                         const float sgm = vg * __builtin_amdgcn_rcpf(1.f + __builtin_amdgcn_exp2f(-vg * LOG2E));
;                         o[j] = sgm * va;
;                     }
;                     if (rho >= 1 && rho <= 62) { u32x2 w; w.x = pk2(o[0], o[1]); w.y = pk2(o[2], o[3]); *(u32x2*)(ACT + (size_t)(row0 + rho) * DFF + ca) = w; }
.LBB0_129:
	s_or_b64 exec, exec, s[56:57]
	v_or_b32_e32 v132, 4, v162
	v_ashrrev_i32_e32 v133, 31, v132
	v_lshlrev_b64 v[148:149], 2, v[132:133]
	v_lshl_add_u64 v[132:133], s[80:81], 0, v[148:149]
	v_lshl_add_u64 v[134:135], s[70:71], 0, v[148:149]
	v_lshl_add_u64 v[140:141], s[24:25], 0, v[148:149]
	v_lshl_add_u64 v[144:145], s[72:73], 0, v[148:149]
	ds_read_b128 v[128:131], v166 offset:16
	ds_read_b128 v[156:159], v166 offset:528
	s_nop 0
	ds_read_b128 v[132:135], v166 offset:1040
	s_nop 0
	ds_read_b128 v[136:139], v166 offset:1552
	s_nop 0
	ds_read_b128 v[140:143], v166 offset:2064
	s_nop 0
	ds_read_b128 v[152:155], v166 offset:2576
	v_lshl_add_u64 v[144:145], s[66:67], 0, v[148:149]
	v_lshl_add_u64 v[148:149], s[68:69], 0, v[148:149]
	ds_read_b128 v[144:147], v166 offset:3088
	v_cndmask_b32_e64 v164, v120, v112, s[10:11]
	ds_read_b128 v[148:151], v166 offset:3600
	v_mov_b32_e32 v182, v185
	v_mov_b32_e32 v200, v185
	v_mov_b32_e32 v183, v185
	v_mov_b32_dpp v182, v164 row_ror:15 row_mask:0xf bank_mask:0xf
	v_cndmask_b32_e64 v164, v88, v80, s[10:11]
	v_cndmask_b32_e64 v165, v122, v114, s[10:11]
	v_mov_b32_e32 v166, v185
	v_mov_b32_dpp v200, v164 row_ror:15 row_mask:0xf bank_mask:0xf
	v_cndmask_b32_e64 v164, v121, v113, s[10:11]
	v_mov_b32_e32 v201, v185
	v_mov_b32_dpp v166, v165 row_ror:15 row_mask:0xf bank_mask:0xf
	v_mov_b32_dpp v183, v164 row_ror:15 row_mask:0xf bank_mask:0xf
	v_cndmask_b32_e64 v164, v89, v81, s[10:11]
	v_cndmask_b32_e64 v165, v90, v82, s[10:11]
	v_mov_b32_e32 v194, v185
	v_cndmask_b32_e64 v195, v123, v115, s[10:11]
	v_mov_b32_e32 v167, v185
	v_mov_b32_e32 v180, v185
	v_mov_b32_e32 v198, v185
	v_mov_b32_e32 v181, v185
	v_mov_b32_e32 v199, v185
	v_mov_b32_dpp v201, v164 row_ror:15 row_mask:0xf bank_mask:0xf
	v_mov_b32_e32 v164, v185
	v_mov_b32_e32 v196, v185
	v_mov_b32_dpp v194, v165 row_ror:15 row_mask:0xf bank_mask:0xf
	v_mov_b32_e32 v165, v185
	v_mov_b32_dpp v167, v195 row_ror:15 row_mask:0xf bank_mask:0xf
	v_mov_b32_e32 v197, v185
	v_cndmask_b32_e64 v202, v91, v83, s[10:11]
	v_mov_b32_e32 v195, v185
	v_mov_b32_dpp v180, v120 row_ror:1 row_mask:0xf bank_mask:0xf
	v_mov_b32_dpp v198, v88 row_ror:1 row_mask:0xf bank_mask:0xf
	v_mov_b32_dpp v181, v121 row_ror:1 row_mask:0xf bank_mask:0xf
	v_mov_b32_dpp v199, v89 row_ror:1 row_mask:0xf bank_mask:0xf
	v_mov_b32_dpp v164, v122 row_ror:1 row_mask:0xf bank_mask:0xf
	v_mov_b32_dpp v196, v90 row_ror:1 row_mask:0xf bank_mask:0xf
	v_mov_b32_dpp v165, v123 row_ror:1 row_mask:0xf bank_mask:0xf
	v_mov_b32_dpp v197, v91 row_ror:1 row_mask:0xf bank_mask:0xf
	v_mov_b32_dpp v195, v202 row_ror:15 row_mask:0xf bank_mask:0xf
	s_and_saveexec_b64 vcc, s[12:13]
	s_cbranch_execz .LBB0_131
	s_waitcnt lgkmcnt(0)
	v_pk_mul_f32 v[224:225], v[88:89], v[152:153]
	v_pk_mul_f32 v[222:223], v[120:121], v[156:157]
	v_pk_fma_f32 v[198:199], v[140:141], v[198:199], v[224:225]
	v_pk_fma_f32 v[180:181], v[128:129], v[180:181], v[222:223]
	s_waitcnt lgkmcnt(0)
	v_pk_fma_f32 v[198:199], v[144:145], v[200:201], v[198:199]
	v_pk_fma_f32 v[180:181], v[132:133], v[182:183], v[180:181]
	s_waitcnt lgkmcnt(0)
	v_pk_add_f32 v[198:199], v[148:149], v[198:199]
	v_pk_add_f32 v[180:181], v[136:137], v[180:181]
	v_mul_f32_e32 v200, 0xbfb8aa3b, v198
	v_exp_f32_e32 v221, v200
	v_mul_f32_e32 v200, 0xbfb8aa3b, v199
	v_exp_f32_e32 v225, v200
	v_pk_mul_f32 v[200:201], v[90:91], v[154:155]
	v_add_f32_e32 v221, 1.0, v221
	v_pk_fma_f32 v[196:197], v[142:143], v[196:197], v[200:201]
	v_rcp_f32_e32 v224, v221
	v_pk_fma_f32 v[194:195], v[146:147], v[194:195], v[196:197]
	v_add_f32_e32 v221, 1.0, v225
	v_pk_add_f32 v[194:195], v[150:151], v[194:195]
	v_rcp_f32_e32 v225, v221
	v_mul_f32_e32 v196, 0xbfb8aa3b, v194
	v_mul_f32_e32 v197, 0xbfb8aa3b, v195
	v_exp_f32_e32 v196, v196
	v_exp_f32_e32 v197, v197
	v_pk_mul_f32 v[182:183], v[198:199], v[224:225]
	v_pk_mul_f32 v[202:203], v[122:123], v[158:159]
	v_pk_mul_f32 v[180:181], v[180:181], v[182:183]
	v_add_f32_e32 v182, 1.0, v196
	v_add_f32_e32 v183, 1.0, v197
	v_rcp_f32_e32 v182, v182
	v_rcp_f32_e32 v183, v183
	v_pk_fma_f32 v[164:165], v[130:131], v[164:165], v[202:203]
	v_readlane_b32 s46, v254, 39
	v_pk_fma_f32 v[164:165], v[134:135], v[166:167], v[164:165]
	v_pk_mul_f32 v[166:167], v[194:195], v[182:183]
	v_pk_add_f32 v[164:165], v[138:139], v[164:165]
	v_readlane_b32 s47, v254, 40
	v_pk_mul_f32 v[164:165], v[164:165], v[166:167]
	s_movk_i32 s0, 0x2c00
	v_cvt_pk_bf16_f32 v167, v164, v165
	v_mov_b64_e32 v[164:165], s[46:47]
	v_mad_i64_i32 v[164:165], s[46:47], v215, s0, v[164:165]
	v_cvt_pk_bf16_f32 v166, v180, v181
	v_lshl_add_u64 v[164:165], v[162:163], 1, v[164:165]
	global_store_dwordx2 v[164:165], v[166:167], off offset:8

; DI unsigned pk2(float lo, float hi) { f32x2 v = {lo, hi}; return __builtin_bit_cast(unsigned, __builtin_convertvector(v, bf16x2v)); }
; DI float dpp_ror1(float v) { return __builtin_bit_cast(float, __builtin_amdgcn_update_dpp(0, __builtin_bit_cast(int, v), 0x121, 0xF, 0xF, false)); }
; DI float dpp_rol1(float v) { return __builtin_bit_cast(float, __builtin_amdgcn_update_dpp(0, __builtin_bit_cast(int, v), 0x12F, 0xF, 0xF, false)); }
;     DI void operator()(const f32x4 (&acc)[2][2][4][2], const Unit& u, int wr, int wc, int fr, int fq) const {
;     ...
;                 for (int m = 0; m < 4; ++m) {
;                     const int rho = 16 * m + fr;
;                     const f32x4 ca_ = acc[ai][0][m][n], cg_ = acc[ai][1][m][n];
;                     const f32x4 ua_ = acc[ai][0][m > 0 ? m - 1 : 0][n], ug_ = acc[ai][1][m > 0 ? m - 1 : 0][n];
;                     const f32x4 da_ = acc[ai][0][m < 3 ? m + 1 : 3][n], dg_ = acc[ai][1][m < 3 ? m + 1 : 3][n];
;                     float o[4];
; #pragma unroll
;                     for (int j = 0; j < 4; ++j) {
;                         const float upa = dpp_ror1(fr == 15 ? ua_[j] : ca_[j]), dna = dpp_rol1(fr == 0 ? da_[j] : ca_[j]);
;                         const float upg = dpp_ror1(fr == 15 ? ug_[j] : cg_[j]), dng = dpp_rol1(fr == 0 ? dg_[j] : cg_[j]);
;                         const float va = wa0[j] * upa + wa1[j] * ca_[j] + wa2[j] * dna + ba[j];
;                         const float vg = wg0[j] * upg + wg1[j] * cg_[j] + wg2[j] * dng + bg[j];
;                         const float sgm = vg * __builtin_amdgcn_rcpf(1.f + __builtin_amdgcn_exp2f(-vg * LOG2E));
;                         o[j] = sgm * va;
;                     }
;                     if (rho >= 1 && rho <= 62) { u32x2 w; w.x = pk2(o[0], o[1]); w.y = pk2(o[2], o[3]); *(u32x2*)(ACT + (size_t)(row0 + rho) * DFF + ca) = w; }
.LBB0_133:
	s_or_b64 exec, exec, s[56:57]
	v_cndmask_b32_e64 v165, v112, v120, s[6:7]
	v_mov_b32_e32 v164, v185
	v_mov_b32_e32 v166, v185
	v_mov_b32_e32 v180, v185
	v_mov_b32_dpp v164, v165 row_ror:1 row_mask:0xf bank_mask:0xf
	v_cndmask_b32_e64 v165, v112, v104, s[10:11]
	v_mov_b32_e32 v182, v185
	v_cndmask_b32_e64 v167, v113, v121, s[6:7]
	v_mov_b32_dpp v166, v165 row_ror:15 row_mask:0xf bank_mask:0xf
	v_cndmask_b32_e64 v165, v80, v88, s[6:7]
	v_cndmask_b32_e64 v181, v113, v105, s[10:11]
	v_cndmask_b32_e64 v183, v81, v89, s[6:7]
	v_mov_b32_dpp v180, v165 row_ror:1 row_mask:0xf bank_mask:0xf
	v_cndmask_b32_e64 v165, v80, v72, s[10:11]
	v_cndmask_b32_e64 v194, v81, v73, s[10:11]
	s_waitcnt lgkmcnt(0)
	v_pk_mul_f32 v[224:225], v[80:81], v[152:153]
	v_mov_b32_dpp v182, v165 row_ror:15 row_mask:0xf bank_mask:0xf
	v_mov_b32_e32 v165, v185
	v_cndmask_b32_e64 v195, v114, v122, s[6:7]
	v_mov_b32_e32 v196, v185
	v_mov_b32_dpp v165, v167 row_ror:1 row_mask:0xf bank_mask:0xf
	v_mov_b32_e32 v167, v185
	v_mov_b32_e32 v198, v185
	v_mov_b32_e32 v200, v185
	v_mov_b32_dpp v167, v181 row_ror:15 row_mask:0xf bank_mask:0xf
	v_mov_b32_e32 v181, v185
	v_cndmask_b32_e64 v197, v115, v123, s[6:7]
	v_cndmask_b32_e64 v199, v115, v107, s[10:11]
	v_mov_b32_dpp v181, v183 row_ror:1 row_mask:0xf bank_mask:0xf
	v_mov_b32_e32 v183, v185
	v_pk_fma_f32 v[180:181], v[140:141], v[180:181], v[224:225]
	v_cndmask_b32_e64 v201, v83, v91, s[6:7]
	v_mov_b32_dpp v183, v194 row_ror:15 row_mask:0xf bank_mask:0xf
	s_waitcnt lgkmcnt(0)
	v_pk_fma_f32 v[180:181], v[144:145], v[182:183], v[180:181]
	v_mov_b32_e32 v194, v185
	s_waitcnt lgkmcnt(0)
	v_pk_add_f32 v[180:181], v[148:149], v[180:181]
	v_pk_mul_f32 v[222:223], v[112:113], v[156:157]
	v_mul_f32_e32 v182, 0xbfb8aa3b, v180
	v_exp_f32_e32 v215, v182
	v_mul_f32_e32 v182, 0xbfb8aa3b, v181
	v_exp_f32_e32 v216, v182
	v_mov_b32_dpp v194, v195 row_ror:1 row_mask:0xf bank_mask:0xf
	v_cndmask_b32_e64 v195, v114, v106, s[10:11]
	v_add_f32_e32 v215, 1.0, v215
	v_rcp_f32_e32 v224, v215
	v_mov_b32_dpp v196, v195 row_ror:15 row_mask:0xf bank_mask:0xf
	v_cndmask_b32_e64 v195, v82, v90, s[6:7]
	v_add_f32_e32 v215, 1.0, v216
	v_rcp_f32_e32 v225, v215
	v_mov_b32_dpp v198, v195 row_ror:1 row_mask:0xf bank_mask:0xf
	v_cndmask_b32_e64 v195, v82, v74, s[10:11]
	v_cndmask_b32_e64 v202, v83, v75, s[10:11]
	v_pk_mul_f32 v[182:183], v[82:83], v[154:155]
	v_mov_b32_dpp v200, v195 row_ror:15 row_mask:0xf bank_mask:0xf
	v_mov_b32_e32 v195, v185
	v_pk_fma_f32 v[164:165], v[128:129], v[164:165], v[222:223]
	v_pk_mul_f32 v[222:223], v[104:105], v[156:157]
	v_mov_b32_dpp v195, v197 row_ror:1 row_mask:0xf bank_mask:0xf
	v_mov_b32_e32 v197, v185
	v_pk_fma_f32 v[164:165], v[132:133], v[166:167], v[164:165]
	v_pk_mul_f32 v[166:167], v[180:181], v[224:225]
	v_mov_b32_dpp v197, v199 row_ror:15 row_mask:0xf bank_mask:0xf
	v_mov_b32_e32 v199, v185
	v_pk_add_f32 v[164:165], v[136:137], v[164:165]
	s_nop 0
	v_mov_b32_dpp v199, v201 row_ror:1 row_mask:0xf bank_mask:0xf
	v_mov_b32_e32 v201, v185
	v_pk_fma_f32 v[180:181], v[142:143], v[198:199], v[182:183]
	v_pk_mul_f32 v[164:165], v[164:165], v[166:167]
	v_mov_b32_dpp v201, v202 row_ror:15 row_mask:0xf bank_mask:0xf
	v_pk_fma_f32 v[180:181], v[146:147], v[200:201], v[180:181]
	v_pk_mul_f32 v[202:203], v[114:115], v[158:159]
	v_pk_add_f32 v[180:181], v[150:151], v[180:181]
	v_cvt_pk_bf16_f32 v164, v164, v165
	v_mul_f32_e32 v182, 0xbfb8aa3b, v180
	v_mul_f32_e32 v183, 0xbfb8aa3b, v181
	v_exp_f32_e32 v182, v182
	v_exp_f32_e32 v183, v183
	v_pk_mul_f32 v[200:201], v[72:73], v[152:153]
	v_mov_b32_e32 v198, v185
	v_add_f32_e32 v166, 1.0, v182
	v_add_f32_e32 v167, 1.0, v183
	v_rcp_f32_e32 v166, v166
	v_rcp_f32_e32 v167, v167
	v_pk_fma_f32 v[182:183], v[130:131], v[194:195], v[202:203]
	v_mov_b32_e32 v194, v185
	v_pk_fma_f32 v[182:183], v[134:135], v[196:197], v[182:183]
	v_pk_mul_f32 v[166:167], v[180:181], v[166:167]
	v_pk_add_f32 v[182:183], v[138:139], v[182:183]
	v_mov_b32_e32 v180, v185
	v_pk_mul_f32 v[166:167], v[182:183], v[166:167]
	v_cndmask_b32_e64 v181, v73, v81, s[6:7]
	v_cvt_pk_bf16_f32 v165, v166, v167
	global_store_dwordx2 v[168:169], v[164:165], off offset:8
	v_cndmask_b32_e64 v165, v104, v112, s[6:7]
	v_mov_b32_e32 v164, v185
	v_mov_b32_e32 v166, v185
	v_mov_b32_e32 v168, v185
	v_mov_b32_dpp v164, v165 row_ror:1 row_mask:0xf bank_mask:0xf
	v_cndmask_b32_e64 v165, v104, v96, s[10:11]
	v_cndmask_b32_e64 v167, v105, v113, s[6:7]
	v_cndmask_b32_e64 v169, v105, v97, s[10:11]
	v_mov_b32_dpp v166, v165 row_ror:15 row_mask:0xf bank_mask:0xf
	v_cndmask_b32_e64 v165, v72, v80, s[6:7]
	v_cndmask_b32_e64 v182, v73, v65, s[10:11]
	v_cndmask_b32_e64 v183, v106, v114, s[6:7]
	v_mov_b32_dpp v168, v165 row_ror:1 row_mask:0xf bank_mask:0xf
	v_cndmask_b32_e64 v165, v72, v64, s[10:11]
	v_mov_b32_e32 v196, v185
	v_cndmask_b32_e64 v195, v107, v115, s[6:7]
	v_mov_b32_dpp v180, v165 row_ror:15 row_mask:0xf bank_mask:0xf
	v_mov_b32_e32 v165, v185
	v_cndmask_b32_e64 v197, v107, v99, s[10:11]
	v_cndmask_b32_e64 v199, v75, v83, s[6:7]
	v_mov_b32_dpp v165, v167 row_ror:1 row_mask:0xf bank_mask:0xf
	v_mov_b32_e32 v167, v185
	v_cndmask_b32_e64 v202, v75, v67, s[10:11]
	v_pk_fma_f32 v[164:165], v[128:129], v[164:165], v[222:223]
	v_mov_b32_dpp v167, v169 row_ror:15 row_mask:0xf bank_mask:0xf
	v_mov_b32_e32 v169, v185
	v_pk_fma_f32 v[164:165], v[132:133], v[166:167], v[164:165]
	s_nop 0
	v_mov_b32_dpp v169, v181 row_ror:1 row_mask:0xf bank_mask:0xf
	v_mov_b32_e32 v181, v185
	v_pk_fma_f32 v[168:169], v[140:141], v[168:169], v[200:201]
	v_pk_add_f32 v[164:165], v[136:137], v[164:165]
	v_mov_b32_dpp v181, v182 row_ror:15 row_mask:0xf bank_mask:0xf
; DI unsigned pk2(float lo, float hi) { f32x2 v = {lo, hi}; return __builtin_bit_cast(unsigned, __builtin_convertvector(v, bf16x2v)); }
; DI float dpp_ror1(float v) { return __builtin_bit_cast(float, __builtin_amdgcn_update_dpp(0, __builtin_bit_cast(int, v), 0x121, 0xF, 0xF, false)); }
; DI float dpp_rol1(float v) { return __builtin_bit_cast(float, __builtin_amdgcn_update_dpp(0, __builtin_bit_cast(int, v), 0x12F, 0xF, 0xF, false)); }
;     DI void operator()(const f32x4 (&acc)[2][2][4][2], const Unit& u, int wr, int wc, int fr, int fq) const {
;     ...
;                 for (int m = 0; m < 4; ++m) {
;                     const int rho = 16 * m + fr;
;                     const f32x4 ca_ = acc[ai][0][m][n], cg_ = acc[ai][1][m][n];
;                     const f32x4 ua_ = acc[ai][0][m > 0 ? m - 1 : 0][n], ug_ = acc[ai][1][m > 0 ? m - 1 : 0][n];
;                     const f32x4 da_ = acc[ai][0][m < 3 ? m + 1 : 3][n], dg_ = acc[ai][1][m < 3 ? m + 1 : 3][n];
;                     float o[4];
; #pragma unroll
;                     for (int j = 0; j < 4; ++j) {
;                         const float upa = dpp_ror1(fr == 15 ? ua_[j] : ca_[j]), dna = dpp_rol1(fr == 0 ? da_[j] : ca_[j]);
;                         const float upg = dpp_ror1(fr == 15 ? ug_[j] : cg_[j]), dng = dpp_rol1(fr == 0 ? dg_[j] : cg_[j]);
;                         const float va = wa0[j] * upa + wa1[j] * ca_[j] + wa2[j] * dna + ba[j];
;                         const float vg = wg0[j] * upg + wg1[j] * cg_[j] + wg2[j] * dng + bg[j];
;                         const float sgm = vg * __builtin_amdgcn_rcpf(1.f + __builtin_amdgcn_exp2f(-vg * LOG2E));
;                         o[j] = sgm * va;
;                     }
;                     if (rho >= 1 && rho <= 62) { u32x2 w; w.x = pk2(o[0], o[1]); w.y = pk2(o[2], o[3]); *(u32x2*)(ACT + (size_t)(row0 + rho) * DFF + ca) = w; }
	v_pk_fma_f32 v[168:169], v[144:145], v[180:181], v[168:169]
	v_mov_b32_e32 v182, v185
	v_pk_add_f32 v[168:169], v[148:149], v[168:169]
	s_nop 0
	v_mul_f32_e32 v180, 0xbfb8aa3b, v168
	v_mul_f32_e32 v201, 0xbfb8aa3b, v169
	v_exp_f32_e32 v200, v180
	v_exp_f32_e32 v201, v201
	v_mov_b32_dpp v182, v183 row_ror:1 row_mask:0xf bank_mask:0xf
	v_cndmask_b32_e64 v183, v106, v98, s[10:11]
	v_add_f32_e32 v200, 1.0, v200
	v_add_f32_e32 v201, 1.0, v201
	v_mov_b32_dpp v194, v183 row_ror:15 row_mask:0xf bank_mask:0xf
	v_cndmask_b32_e64 v183, v74, v82, s[6:7]
	v_rcp_f32_e32 v200, v200
	v_rcp_f32_e32 v201, v201
	v_mov_b32_dpp v196, v183 row_ror:1 row_mask:0xf bank_mask:0xf
	v_cndmask_b32_e64 v183, v74, v66, s[10:11]
	v_pk_mul_f32 v[180:181], v[74:75], v[154:155]
	v_pk_mul_f32 v[166:167], v[168:169], v[200:201]
	v_mov_b32_dpp v198, v183 row_ror:15 row_mask:0xf bank_mask:0xf
	v_mov_b32_e32 v183, v185
	v_pk_mul_f32 v[164:165], v[164:165], v[166:167]
	s_nop 0
	v_mov_b32_dpp v183, v195 row_ror:1 row_mask:0xf bank_mask:0xf
	v_mov_b32_e32 v195, v185
	v_cvt_pk_bf16_f32 v164, v164, v165
	s_nop 0
	v_mov_b32_dpp v195, v197 row_ror:15 row_mask:0xf bank_mask:0xf
	v_mov_b32_e32 v197, v185
	s_nop 1
	v_mov_b32_dpp v197, v199 row_ror:1 row_mask:0xf bank_mask:0xf
	v_mov_b32_e32 v199, v185
	v_pk_fma_f32 v[168:169], v[142:143], v[196:197], v[180:181]
	v_mov_b32_e32 v196, v185
	v_mov_b32_dpp v199, v202 row_ror:15 row_mask:0xf bank_mask:0xf
	v_pk_fma_f32 v[168:169], v[146:147], v[198:199], v[168:169]
	v_pk_mul_f32 v[202:203], v[106:107], v[158:159]
	v_pk_add_f32 v[168:169], v[150:151], v[168:169]
	v_mov_b32_e32 v197, v185
	v_mul_f32_e32 v180, 0xbfb8aa3b, v168
	v_mul_f32_e32 v181, 0xbfb8aa3b, v169
	v_exp_f32_e32 v180, v180
	v_exp_f32_e32 v181, v181
	v_mov_b32_dpp v196, v64 row_ror:15 row_mask:0xf bank_mask:0xf
	v_mov_b32_dpp v197, v65 row_ror:15 row_mask:0xf bank_mask:0xf
	v_add_f32_e32 v166, 1.0, v180
	v_add_f32_e32 v167, 1.0, v181
	v_rcp_f32_e32 v166, v166
	v_rcp_f32_e32 v167, v167
	v_pk_fma_f32 v[180:181], v[130:131], v[182:183], v[202:203]
	v_cndmask_b32_e64 v183, v67, v75, s[6:7]
	v_pk_fma_f32 v[180:181], v[134:135], v[194:195], v[180:181]
	v_pk_mul_f32 v[166:167], v[168:169], v[166:167]
	v_pk_add_f32 v[180:181], v[138:139], v[180:181]
	v_mov_b32_e32 v168, v185
	v_pk_mul_f32 v[166:167], v[180:181], v[166:167]
	v_mov_b32_e32 v194, v185
	v_cvt_pk_bf16_f32 v165, v166, v167
	global_store_dwordx2 v[172:173], v[164:165], off offset:8
	v_cndmask_b32_e64 v164, v96, v104, s[6:7]
	v_mov_b32_e32 v169, v185
	v_mov_b32_e32 v195, v185
	v_mov_b32_dpp v168, v164 row_ror:1 row_mask:0xf bank_mask:0xf
	v_cndmask_b32_e64 v164, v64, v72, s[6:7]
	v_cndmask_b32_e64 v165, v98, v106, s[6:7]
	v_mov_b32_e32 v180, v185
	v_mov_b32_dpp v194, v164 row_ror:1 row_mask:0xf bank_mask:0xf
	v_cndmask_b32_e64 v164, v97, v105, s[6:7]
	v_cndmask_b32_e64 v167, v99, v107, s[6:7]
	v_mov_b32_e32 v181, v185
	v_mov_b32_dpp v169, v164 row_ror:1 row_mask:0xf bank_mask:0xf
	v_cndmask_b32_e64 v164, v65, v73, s[6:7]
	v_mov_b32_e32 v172, v185
	v_mov_b32_e32 v173, v185
	v_mov_b32_dpp v195, v164 row_ror:1 row_mask:0xf bank_mask:0xf
	v_mov_b32_e32 v164, v185
	v_mov_b32_e32 v166, v185
	v_mov_b32_e32 v182, v185
	v_mov_b32_dpp v164, v165 row_ror:1 row_mask:0xf bank_mask:0xf
	v_cndmask_b32_e64 v165, v66, v74, s[6:7]
	v_mov_b32_dpp v181, v183 row_ror:1 row_mask:0xf bank_mask:0xf
	v_mov_b32_e32 v183, v185
	v_mov_b32_dpp v180, v165 row_ror:1 row_mask:0xf bank_mask:0xf
	v_mov_b32_e32 v165, v185
	v_mov_b32_dpp v172, v96 row_ror:15 row_mask:0xf bank_mask:0xf
	v_mov_b32_dpp v173, v97 row_ror:15 row_mask:0xf bank_mask:0xf
	v_mov_b32_dpp v165, v167 row_ror:1 row_mask:0xf bank_mask:0xf
	v_mov_b32_e32 v167, v185
	v_mov_b32_dpp v166, v98 row_ror:15 row_mask:0xf bank_mask:0xf
	v_mov_b32_dpp v182, v66 row_ror:15 row_mask:0xf bank_mask:0xf
	v_mov_b32_dpp v167, v99 row_ror:15 row_mask:0xf bank_mask:0xf
	v_mov_b32_dpp v183, v67 row_ror:15 row_mask:0xf bank_mask:0xf
	s_and_saveexec_b64 s[44:45], s[8:9]
	s_cbranch_execz .LBB0_135
	v_pk_mul_f32 v[202:203], v[64:65], v[152:153]
	v_pk_mul_f32 v[200:201], v[96:97], v[156:157]
	v_pk_fma_f32 v[194:195], v[140:141], v[194:195], v[202:203]
	v_pk_fma_f32 v[168:169], v[128:129], v[168:169], v[200:201]
	v_pk_fma_f32 v[194:195], v[144:145], v[196:197], v[194:195]
	v_pk_fma_f32 v[168:169], v[132:133], v[172:173], v[168:169]
	v_pk_add_f32 v[194:195], v[148:149], v[194:195]
	v_pk_add_f32 v[168:169], v[136:137], v[168:169]
	v_mul_f32_e32 v196, 0xbfb8aa3b, v194
	v_exp_f32_e32 v202, v196
	v_mul_f32_e32 v196, 0xbfb8aa3b, v195
	v_exp_f32_e32 v203, v196
	v_pk_mul_f32 v[196:197], v[66:67], v[154:155]
	v_add_f32_e32 v202, 1.0, v202
	v_pk_fma_f32 v[180:181], v[142:143], v[180:181], v[196:197]
	v_add_f32_e32 v203, 1.0, v203
	v_pk_fma_f32 v[180:181], v[146:147], v[182:183], v[180:181]
	v_rcp_f32_e32 v202, v202
	v_pk_add_f32 v[180:181], v[150:151], v[180:181]
	v_rcp_f32_e32 v203, v203
	v_mul_f32_e32 v182, 0xbfb8aa3b, v180
	v_mul_f32_e32 v183, 0xbfb8aa3b, v181
	v_exp_f32_e32 v182, v182
	v_exp_f32_e32 v183, v183
	v_pk_mul_f32 v[172:173], v[194:195], v[202:203]
	v_pk_mul_f32 v[198:199], v[98:99], v[158:159]
	v_pk_mul_f32 v[168:169], v[168:169], v[172:173]
	v_add_f32_e32 v172, 1.0, v182
	v_add_f32_e32 v173, 1.0, v183
	v_rcp_f32_e32 v172, v172
	v_rcp_f32_e32 v173, v173
	v_pk_fma_f32 v[164:165], v[130:131], v[164:165], v[198:199]
	v_readlane_b32 s46, v254, 39
	v_pk_fma_f32 v[164:165], v[134:135], v[166:167], v[164:165]
	v_pk_mul_f32 v[166:167], v[180:181], v[172:173]
	v_pk_add_f32 v[164:165], v[138:139], v[164:165]
	v_readlane_b32 s47, v254, 40
	v_pk_mul_f32 v[164:165], v[164:165], v[166:167]
	s_movk_i32 s0, 0x2c00
	v_cvt_pk_bf16_f32 v167, v164, v165
	v_mov_b64_e32 v[164:165], s[46:47]
	v_mad_i64_i32 v[164:165], s[46:47], v217, s0, v[164:165]
	v_cvt_pk_bf16_f32 v166, v168, v169
	v_lshl_add_u64 v[164:165], v[162:163], 1, v[164:165]
	global_store_dwordx2 v[164:165], v[166:167], off offset:8
